# v105 + producers rebalanced: the P3 gate/up weight-conversion items assigned in reverse wave order (heaviest workgroups get 7 items instead of 8)
# speedup vs baseline: 1.0037x; 1.0024x over previous
.LBB0_338:
	s_lshl_b32 s0, s3, 3
	v_readlane_b32 s1, v242, 28
	s_add_i32 s22, s1, s0
	s_sub_i32 s22, 0x5ff, s22
	s_cmpk_gt_i32 s22, 0x2bff
	s_waitcnt vmcnt(63) expcnt(7) lgkmcnt(15)
	s_barrier
	s_cbranch_scc1 .LBB0_345
	s_mul_hi_u32 s0, s22, 0xba2e8ba3
	s_lshr_b32 s10, s0, 8
	s_mul_i32 s0, s10, 0x160
	s_sub_i32 s0, s22, s0
	s_lshl_b32 s0, s0, 5
	s_mov_b32 s1, 0
	s_mov_b64 s[26:27], s[16:17]
	v_readlane_b32 s12, v242, 0
	s_lshl_b32 s3, s24, 3
	s_lshl_b64 s[0:1], s[0:1], 2
	v_readlane_b32 s16, v242, 4
	v_readlane_b32 s17, v242, 5
	s_add_u32 s0, s16, s0
	s_waitcnt vmcnt(34)
	v_and_b32_e32 v38, 7, v143
	v_lshrrev_b32_e32 v1, 3, v142
	s_addc_u32 s1, s17, s1
	v_lshlrev_b32_e32 v36, 4, v38
	v_mov_b32_e32 v37, 0
	s_waitcnt vmcnt(20)
	v_lshl_add_u64 v[26:27], s[0:1], 0, v[36:37]
	s_waitcnt vmcnt(10)
	v_lshl_or_b32 v30, s10, 6, v1
	s_mov_b32 s12, 0xb000
	v_mad_u64_u32 v[2:3], s[0:1], v30, s12, v[26:27]
	v_or_b32_e32 v4, 8, v30
	v_or_b32_e32 v10, 16, v30
	v_or_b32_e32 v12, 24, v30
	v_or_b32_e32 v18, 32, v30
	v_or_b32_e32 v20, 40, v30
	v_or_b32_e32 v28, 48, v30
	v_or_b32_e32 v30, 56, v30
	v_mad_u64_u32 v[6:7], s[0:1], v4, s12, v[26:27]
	v_mad_u64_u32 v[10:11], s[0:1], v10, s12, v[26:27]
	v_mad_u64_u32 v[14:15], s[0:1], v12, s12, v[26:27]
	v_mad_u64_u32 v[18:19], s[0:1], v18, s12, v[26:27]
	v_mad_u64_u32 v[22:23], s[0:1], v20, s12, v[26:27]
	v_mad_u64_u32 v[28:29], s[0:1], v28, s12, v[26:27]
	s_waitcnt vmcnt(9)
	v_mad_u64_u32 v[30:31], s[0:1], v30, s12, v[26:27]
	global_load_dwordx4 v[2:5], v[2:3], off nt
	s_nop 0
	global_load_dwordx4 v[6:9], v[6:7], off nt
	s_nop 0
	global_load_dwordx4 v[10:13], v[10:11], off nt
	s_nop 0
	global_load_dwordx4 v[14:17], v[14:15], off nt
	s_nop 0
	global_load_dwordx4 v[18:21], v[18:19], off nt
	s_nop 0
	global_load_dwordx4 v[22:25], v[22:23], off nt
	s_nop 0
	global_load_dwordx4 v[26:29], v[28:29], off nt
	s_nop 0
	global_load_dwordx4 v[30:33], v[30:31], off nt
	v_readlane_b32 s0, v242, 29
	v_readlane_b32 s13, v242, 1
	v_mul_u32_u24_e32 v38, 0x420, v38
	v_add_u32_e32 v42, s0, v36
	v_lshlrev_b32_e32 v39, 2, v1
	v_mul_u32_u24_e32 v43, 0x84, v1
	s_waitcnt vmcnt(13)
	v_lshl_add_u64 v[34:35], s[16:17], 0, v[36:37]
	s_mov_b64 s[16:17], s[26:27]
	v_lshl_add_u64 v[36:37], s[6:7], 0, v[36:37]
	v_add3_u32 v38, s0, v38, v39
	v_or_b32_e32 v39, 8, v1
	v_or_b32_e32 v40, 16, v1
	v_or_b32_e32 v41, 24, v1
	s_lshl_b32 s23, s22, 5
	s_lshl_b32 s13, s24, 8
	v_add_u32_e32 v42, v42, v43
	v_readlane_b32 s14, v242, 2
	v_readlane_b32 s15, v242, 3
	v_readlane_b32 s18, v242, 6
	v_readlane_b32 s19, v242, 7
	s_branch .LBB0_341
